# grid barrier 4 split-phase for workgroups whose phase-4 work starts with dilated-attention items: they wait for the release only before the first item's output stores (which overlay a phase-3 input)
# speedup vs baseline: 1.0514x; 1.0054x over previous
.LBB0_480:
	s_or_b64 exec, exec, s[0:1]
	v_mov_b32_e32 v184, v0
	s_waitcnt lgkmcnt(0)
	s_barrier
	s_cmpk_gt_u32 s64, 0x7f
	s_cselect_b32 s98, 0, 1
	s_nop 0
	v_readfirstlane_b32 s54, v184
	s_ashr_i32 s0, s54, 6
	s_cmpk_gt_i32 s64, 0x7f
	v_writelane_b32 v254, s0, 27
	s_cselect_b64 s[0:1], -1, 0
	v_writelane_b32 v254, s0, 35
	v_and_b32_e32 v183, 63, v184
	s_and_b64 vcc, exec, s[0:1]
	v_writelane_b32 v254, s1, 36
	s_cbranch_vccz .LBB0_497
	s_cmpk_gt_u32 s64, 0x8f
	s_mov_b64 s[2:3], -1
	v_writelane_b32 v254, s54, 54
	s_cbranch_scc1 .LBB0_498
	s_mov_b64 s[4:5], 0
	s_andn2_b64 vcc, exec, s[2:3]
	s_mov_b64 s[0:1], 0
	s_cbranch_vccz .LBB0_580

.LBB0_536:
	s_waitcnt lgkmcnt(0)
	v_cmp_lt_i32_e32 vcc, v5, v6
	v_add_u32_e32 v13, v158, v130
	s_nop 0
	v_cndmask_b32_e32 v4, v4, v5, vcc
	v_lshlrev_b32_e32 v4, 2, v4
	ds_bpermute_b32 v4, v4, v7
	s_waitcnt lgkmcnt(0)
	v_add_f32_e32 v5, v7, v4
	v_div_scale_f32 v4, s[70:71], v5, v5, 1.0
	v_rcp_f32_e32 v6, v4
	v_log_f32_e32 v12, v5
	v_fma_f32 v7, -v4, v6, 1.0
	v_fmac_f32_e32 v6, v7, v6
	v_div_scale_f32 v7, vcc, 1.0, v5, 1.0
	v_mul_f32_e32 v8, v7, v6
	v_fma_f32 v9, -v4, v8, v7
	v_fmac_f32_e32 v8, v9, v6
	v_fma_f32 v4, -v4, v8, v7
	v_div_fmas_f32 v4, v4, v6, v8
	v_div_fixup_f32 v4, v4, v5, 1.0
	v_pk_mul_f32 v[6:7], v[82:83], v[4:5] op_sel_hi:[1,0]
	v_pk_mul_f32 v[8:9], v[84:85], v[4:5] op_sel_hi:[1,0]
	v_cvt_pk_bf16_f32 v6, v6, v7
	v_cvt_pk_bf16_f32 v7, v8, v9
	v_pk_mul_f32 v[8:9], v[86:87], v[4:5] op_sel_hi:[1,0]
	v_pk_mul_f32 v[10:11], v[88:89], v[4:5] op_sel_hi:[1,0]
	v_cvt_pk_bf16_f32 v8, v8, v9
	v_cvt_pk_bf16_f32 v9, v10, v11
	ds_write2_b64 v13, v[6:7], v[8:9] offset1:2
	v_pk_mul_f32 v[6:7], v[90:91], v[4:5] op_sel_hi:[1,0]
	v_pk_mul_f32 v[8:9], v[92:93], v[4:5] op_sel_hi:[1,0]
	v_cvt_pk_bf16_f32 v6, v6, v7
	v_cvt_pk_bf16_f32 v7, v8, v9
	v_pk_mul_f32 v[8:9], v[94:95], v[4:5] op_sel_hi:[1,0]
	v_pk_mul_f32 v[10:11], v[96:97], v[4:5] op_sel_hi:[1,0]
	v_cvt_pk_bf16_f32 v8, v8, v9
	v_cvt_pk_bf16_f32 v9, v10, v11
	ds_write2_b64 v13, v[6:7], v[8:9] offset0:4 offset1:6
	v_pk_mul_f32 v[6:7], v[66:67], v[4:5] op_sel_hi:[1,0]
	v_pk_mul_f32 v[8:9], v[68:69], v[4:5] op_sel_hi:[1,0]
	v_cvt_pk_bf16_f32 v6, v6, v7
	v_cvt_pk_bf16_f32 v7, v8, v9
	v_pk_mul_f32 v[8:9], v[70:71], v[4:5] op_sel_hi:[1,0]
	v_pk_mul_f32 v[10:11], v[72:73], v[4:5] op_sel_hi:[1,0]
	v_cvt_pk_bf16_f32 v8, v8, v9
	v_cvt_pk_bf16_f32 v9, v10, v11
	ds_write2_b64 v13, v[6:7], v[8:9] offset0:8 offset1:10
	v_pk_mul_f32 v[6:7], v[74:75], v[4:5] op_sel_hi:[1,0]
	v_pk_mul_f32 v[8:9], v[76:77], v[4:5] op_sel_hi:[1,0]
	v_cvt_pk_bf16_f32 v6, v6, v7
	v_cvt_pk_bf16_f32 v7, v8, v9
	v_pk_mul_f32 v[8:9], v[78:79], v[4:5] op_sel_hi:[1,0]
	v_pk_mul_f32 v[4:5], v[80:81], v[4:5] op_sel_hi:[1,0]
	v_cvt_pk_bf16_f32 v8, v8, v9
	v_cvt_pk_bf16_f32 v9, v4, v5
	v_add_f32_e32 v2, v2, v12
	ds_write2_b64 v13, v[6:7], v[8:9] offset0:12 offset1:14
	s_and_saveexec_b64 s[70:71], s[68:69]
	v_add_u32_e32 v4, s6, v143
	ds_write_b32 v4, v2 offset:4608
	s_or_b64 exec, exec, s[70:71]
	s_cmp_lg_u32 s98, 0
	s_cbranch_scc1 .Lsplit4_go0
	s_mov_b64 s[100:101], exec
	v_readlane_b32 s99, v254, 6
	s_nop 3
	s_mov_b32 exec_lo, s99
	s_mov_b32 exec_hi, 0
	s_cbranch_execz .Lsplit4_join0
	v_mov_b32_e32 v240, 0x7000
	v_mov_b32_e32 v242, 0
.Lsplit4_spin0:
	global_load_dword v241, v240, s[82:83] offset:1280 sc1
	s_waitcnt vmcnt(0)
	v_add_u32_e32 v242, 1, v242
	v_readfirstlane_b32 s99, v241
	s_nop 3
	s_cmp_ge_u32 s99, 4
	s_cbranch_scc1 .Lsplit4_join0
	s_sleep 1
	v_readfirstlane_b32 s99, v242
	s_nop 3
	s_cmp_lt_u32 s99, 0x40001
	s_cbranch_scc1 .Lsplit4_spin0
	v_mov_b32_e32 v241, 1
	v_mov_b32_e32 v242, 0x4000
	global_atomic_add v242, v241, s[82:83] offset:512
	s_waitcnt vmcnt(0)
.Lsplit4_join0:
	s_mov_b64 exec, s[100:101]
	s_barrier
	s_mov_b32 s98, 1
.Lsplit4_go0:
	s_lshl_b32 s0, s0, 2
	s_or_b32 s0, s0, s87
	v_or_b32_e32 v4, s86, v131
	s_lshl_b64 s[70:71], s[0:1], 12
	v_ashrrev_i32_e32 v5, 31, v4
	v_lshl_add_u64 v[4:5], s[70:71], 0, v[4:5]
	s_waitcnt lgkmcnt(0)
	v_lshlrev_b64 v[4:5], 7, v[4:5]
	v_add_u32_e32 v10, v159, v150
	v_lshl_add_u64 v[8:9], v[134:135], 0, v[4:5]
	ds_read_b128 v[4:7], v10
	s_waitcnt lgkmcnt(0)
	global_store_dwordx4 v[8:9], v[4:7], off sc1
	s_nop 1
	v_or_b32_e32 v4, s86, v151
	v_ashrrev_i32_e32 v5, 31, v4
	v_lshl_add_u64 v[4:5], s[70:71], 0, v[4:5]
	v_lshlrev_b64 v[4:5], 7, v[4:5]
	v_lshl_add_u64 v[8:9], v[134:135], 0, v[4:5]
	ds_read_b128 v[4:7], v10 offset:1152
	s_waitcnt lgkmcnt(0)
	global_store_dwordx4 v[8:9], v[4:7], off sc1
	s_nop 1
	v_or_b32_e32 v4, s86, v152
	v_ashrrev_i32_e32 v5, 31, v4
	v_lshl_add_u64 v[4:5], s[70:71], 0, v[4:5]
	v_lshlrev_b64 v[4:5], 7, v[4:5]
	v_lshl_add_u64 v[8:9], v[134:135], 0, v[4:5]
	ds_read_b128 v[4:7], v10 offset:2304
	s_waitcnt lgkmcnt(0)
	global_store_dwordx4 v[8:9], v[4:7], off sc1
	s_nop 1
	v_or_b32_e32 v4, s86, v153
	v_ashrrev_i32_e32 v5, 31, v4
	v_lshl_add_u64 v[4:5], s[70:71], 0, v[4:5]
	v_lshlrev_b64 v[4:5], 7, v[4:5]
	v_lshl_add_u64 v[8:9], v[134:135], 0, v[4:5]
	ds_read_b128 v[4:7], v10 offset:3456
	s_waitcnt lgkmcnt(0)
	global_store_dwordx4 v[8:9], v[4:7], off sc1
	s_nop 1
	s_and_saveexec_b64 s[84:85], s[68:69]
	s_cbranch_execz .LBB0_540
	s_lshl_b64 s[70:71], s[70:71], 2
	v_readlane_b32 s0, v254, 46
	s_add_u32 s70, s0, s70
	v_readlane_b32 s0, v254, 50
	s_addc_u32 s71, s0, s71
	v_ashrrev_i32_e32 v141, 31, v140
	v_lshl_add_u64 v[4:5], v[140:141], 2, s[70:71]
	global_store_dword v[4:5], v2, off sc1

.LBB0_575:
	s_waitcnt lgkmcnt(0)
	v_cmp_lt_i32_e32 vcc, v4, v6
	v_add_u32_e32 v13, v158, v130
	s_nop 0
	v_cndmask_b32_e32 v4, v5, v4, vcc
	v_lshlrev_b32_e32 v4, 2, v4
	ds_bpermute_b32 v4, v4, v7
	s_waitcnt lgkmcnt(0)
	v_add_f32_e32 v5, v7, v4
	v_div_scale_f32 v4, s[84:85], v5, v5, 1.0
	v_rcp_f32_e32 v6, v4
	v_log_f32_e32 v12, v5
	v_fma_f32 v7, -v4, v6, 1.0
	v_fmac_f32_e32 v6, v7, v6
	v_div_scale_f32 v7, vcc, 1.0, v5, 1.0
	v_mul_f32_e32 v8, v7, v6
	v_fma_f32 v9, -v4, v8, v7
	v_fmac_f32_e32 v8, v9, v6
	v_fma_f32 v4, -v4, v8, v7
	v_div_fmas_f32 v4, v4, v6, v8
	v_div_fixup_f32 v4, v4, v5, 1.0
	v_pk_mul_f32 v[6:7], v[82:83], v[4:5] op_sel_hi:[1,0]
	v_pk_mul_f32 v[8:9], v[84:85], v[4:5] op_sel_hi:[1,0]
	v_cvt_pk_bf16_f32 v6, v6, v7
	v_cvt_pk_bf16_f32 v7, v8, v9
	v_pk_mul_f32 v[8:9], v[86:87], v[4:5] op_sel_hi:[1,0]
	v_pk_mul_f32 v[10:11], v[88:89], v[4:5] op_sel_hi:[1,0]
	v_cvt_pk_bf16_f32 v8, v8, v9
	v_cvt_pk_bf16_f32 v9, v10, v11
	ds_write2_b64 v13, v[6:7], v[8:9] offset1:2
	v_pk_mul_f32 v[6:7], v[90:91], v[4:5] op_sel_hi:[1,0]
	v_pk_mul_f32 v[8:9], v[92:93], v[4:5] op_sel_hi:[1,0]
	v_cvt_pk_bf16_f32 v6, v6, v7
	v_cvt_pk_bf16_f32 v7, v8, v9
	v_pk_mul_f32 v[8:9], v[94:95], v[4:5] op_sel_hi:[1,0]
	v_pk_mul_f32 v[10:11], v[96:97], v[4:5] op_sel_hi:[1,0]
	v_cvt_pk_bf16_f32 v8, v8, v9
	v_cvt_pk_bf16_f32 v9, v10, v11
	ds_write2_b64 v13, v[6:7], v[8:9] offset0:4 offset1:6
	v_pk_mul_f32 v[6:7], v[66:67], v[4:5] op_sel_hi:[1,0]
	v_pk_mul_f32 v[8:9], v[68:69], v[4:5] op_sel_hi:[1,0]
	v_cvt_pk_bf16_f32 v6, v6, v7
	v_cvt_pk_bf16_f32 v7, v8, v9
	v_pk_mul_f32 v[8:9], v[70:71], v[4:5] op_sel_hi:[1,0]
	v_pk_mul_f32 v[10:11], v[72:73], v[4:5] op_sel_hi:[1,0]
	v_cvt_pk_bf16_f32 v8, v8, v9
	v_cvt_pk_bf16_f32 v9, v10, v11
	ds_write2_b64 v13, v[6:7], v[8:9] offset0:8 offset1:10
	v_pk_mul_f32 v[6:7], v[74:75], v[4:5] op_sel_hi:[1,0]
	v_pk_mul_f32 v[8:9], v[76:77], v[4:5] op_sel_hi:[1,0]
	v_cvt_pk_bf16_f32 v6, v6, v7
	v_cvt_pk_bf16_f32 v7, v8, v9
	v_pk_mul_f32 v[8:9], v[78:79], v[4:5] op_sel_hi:[1,0]
	v_pk_mul_f32 v[4:5], v[80:81], v[4:5] op_sel_hi:[1,0]
	v_cvt_pk_bf16_f32 v8, v8, v9
	v_cvt_pk_bf16_f32 v9, v4, v5
	v_add_f32_e32 v2, v2, v12
	ds_write2_b64 v13, v[6:7], v[8:9] offset0:12 offset1:14
	s_and_saveexec_b64 s[84:85], s[68:69]
	v_add_u32_e32 v4, s6, v143
	ds_write_b32 v4, v2 offset:4608
	s_or_b64 exec, exec, s[84:85]
	s_cmp_lg_u32 s98, 0
	s_cbranch_scc1 .Lsplit4_go1
	s_mov_b64 s[100:101], exec
	v_readlane_b32 s99, v254, 6
	s_nop 3
	s_mov_b32 exec_lo, s99
	s_mov_b32 exec_hi, 0
	s_cbranch_execz .Lsplit4_join1
	v_mov_b32_e32 v240, 0x7000
	v_mov_b32_e32 v242, 0

.Lsplit4_go1:
	s_lshl_b32 s70, s70, 4
	s_or_b32 s70, s70, s33
	s_ashr_i32 s71, s70, 31
	v_or_b32_e32 v4, s0, v131
	s_lshl_b64 s[70:71], s[70:71], 10
	v_ashrrev_i32_e32 v5, 31, v4
	v_lshl_add_u64 v[4:5], s[70:71], 0, v[4:5]
	s_waitcnt lgkmcnt(0)
	v_lshlrev_b64 v[4:5], 7, v[4:5]
	v_add_u32_e32 v10, v159, v150
	v_lshl_add_u64 v[8:9], v[136:137], 0, v[4:5]
	ds_read_b128 v[4:7], v10
	s_waitcnt lgkmcnt(0)
	global_store_dwordx4 v[8:9], v[4:7], off sc1
	s_nop 1
	v_or_b32_e32 v4, s0, v151
	v_ashrrev_i32_e32 v5, 31, v4
	v_lshl_add_u64 v[4:5], s[70:71], 0, v[4:5]
	v_lshlrev_b64 v[4:5], 7, v[4:5]
	v_lshl_add_u64 v[8:9], v[136:137], 0, v[4:5]
	ds_read_b128 v[4:7], v10 offset:1152
	s_waitcnt lgkmcnt(0)
	global_store_dwordx4 v[8:9], v[4:7], off sc1
	s_nop 1
	v_or_b32_e32 v4, s0, v152
	v_ashrrev_i32_e32 v5, 31, v4
	v_lshl_add_u64 v[4:5], s[70:71], 0, v[4:5]
	v_lshlrev_b64 v[4:5], 7, v[4:5]
	v_lshl_add_u64 v[8:9], v[136:137], 0, v[4:5]
	ds_read_b128 v[4:7], v10 offset:2304
	s_waitcnt lgkmcnt(0)
	global_store_dwordx4 v[8:9], v[4:7], off sc1
	s_nop 1
	v_or_b32_e32 v4, s0, v153
	v_ashrrev_i32_e32 v5, 31, v4
	v_lshl_add_u64 v[4:5], s[70:71], 0, v[4:5]
	v_lshlrev_b64 v[4:5], 7, v[4:5]
	v_lshl_add_u64 v[8:9], v[136:137], 0, v[4:5]
	ds_read_b128 v[4:7], v10 offset:3456
	s_waitcnt lgkmcnt(0)
	global_store_dwordx4 v[8:9], v[4:7], off sc1
	s_nop 1
	s_and_saveexec_b64 s[84:85], s[68:69]
	s_cbranch_execz .LBB0_500
	s_lshl_b64 s[70:71], s[70:71], 2
	v_readlane_b32 s0, v254, 56
	s_add_u32 s70, s0, s70
	v_readlane_b32 s0, v254, 58
	s_addc_u32 s71, s0, s71
	v_ashrrev_i32_e32 v141, 31, v140
	v_lshl_add_u64 v[4:5], v[140:141], 2, s[70:71]
	global_store_dword v[4:5], v2, off sc1
	s_branch .LBB0_500

.LBB0_614:
	s_waitcnt lgkmcnt(0)
	v_cmp_lt_i32_e32 vcc, v4, v6
	s_nop 1
	v_cndmask_b32_e32 v4, v5, v4, vcc
	v_lshlrev_b32_e32 v4, 2, v4
	ds_bpermute_b32 v4, v4, v7
	s_waitcnt lgkmcnt(0)
	v_add_f32_e32 v5, v7, v4
	v_div_scale_f32 v4, s[86:87], v5, v5, 1.0
	v_rcp_f32_e32 v6, v4
	v_log_f32_e32 v12, v5
	v_fma_f32 v7, -v4, v6, 1.0
	v_fmac_f32_e32 v6, v7, v6
	v_div_scale_f32 v7, vcc, 1.0, v5, 1.0
	v_mul_f32_e32 v8, v7, v6
	v_fma_f32 v9, -v4, v8, v7
	v_fmac_f32_e32 v8, v9, v6
	v_fma_f32 v4, -v4, v8, v7
	v_div_fmas_f32 v4, v4, v6, v8
	v_div_fixup_f32 v4, v4, v5, 1.0
	v_pk_mul_f32 v[6:7], v[82:83], v[4:5] op_sel_hi:[1,0]
	v_pk_mul_f32 v[8:9], v[84:85], v[4:5] op_sel_hi:[1,0]
	v_cvt_pk_bf16_f32 v6, v6, v7
	v_cvt_pk_bf16_f32 v7, v8, v9
	v_pk_mul_f32 v[8:9], v[86:87], v[4:5] op_sel_hi:[1,0]
	v_pk_mul_f32 v[10:11], v[88:89], v[4:5] op_sel_hi:[1,0]
	v_cvt_pk_bf16_f32 v8, v8, v9
	v_cvt_pk_bf16_f32 v9, v10, v11
	ds_write2_b64 v154, v[6:7], v[8:9] offset1:2
	v_pk_mul_f32 v[6:7], v[90:91], v[4:5] op_sel_hi:[1,0]
	v_pk_mul_f32 v[8:9], v[92:93], v[4:5] op_sel_hi:[1,0]
	v_cvt_pk_bf16_f32 v6, v6, v7
	v_cvt_pk_bf16_f32 v7, v8, v9
	v_pk_mul_f32 v[8:9], v[94:95], v[4:5] op_sel_hi:[1,0]
	v_pk_mul_f32 v[10:11], v[96:97], v[4:5] op_sel_hi:[1,0]
	v_cvt_pk_bf16_f32 v8, v8, v9
	v_cvt_pk_bf16_f32 v9, v10, v11
	ds_write2_b64 v154, v[6:7], v[8:9] offset0:4 offset1:6
	v_pk_mul_f32 v[6:7], v[66:67], v[4:5] op_sel_hi:[1,0]
	v_pk_mul_f32 v[8:9], v[68:69], v[4:5] op_sel_hi:[1,0]
	v_cvt_pk_bf16_f32 v6, v6, v7
	v_cvt_pk_bf16_f32 v7, v8, v9
	v_pk_mul_f32 v[8:9], v[70:71], v[4:5] op_sel_hi:[1,0]
	v_pk_mul_f32 v[10:11], v[72:73], v[4:5] op_sel_hi:[1,0]
	v_cvt_pk_bf16_f32 v8, v8, v9
	v_cvt_pk_bf16_f32 v9, v10, v11
	ds_write2_b64 v154, v[6:7], v[8:9] offset0:8 offset1:10
	v_pk_mul_f32 v[6:7], v[74:75], v[4:5] op_sel_hi:[1,0]
	v_pk_mul_f32 v[8:9], v[76:77], v[4:5] op_sel_hi:[1,0]
	v_cvt_pk_bf16_f32 v6, v6, v7
	v_cvt_pk_bf16_f32 v7, v8, v9
	v_pk_mul_f32 v[8:9], v[78:79], v[4:5] op_sel_hi:[1,0]
	v_pk_mul_f32 v[4:5], v[80:81], v[4:5] op_sel_hi:[1,0]
	v_cvt_pk_bf16_f32 v8, v8, v9
	v_cvt_pk_bf16_f32 v9, v4, v5
	v_add_f32_e32 v2, v2, v12
	ds_write2_b64 v154, v[6:7], v[8:9] offset0:12 offset1:14
	s_and_saveexec_b64 s[86:87], s[68:69]
	v_add_u32_e32 v4, s71, v140
	ds_write_b32 v4, v2 offset:4608
	s_or_b64 exec, exec, s[86:87]
	s_cmp_lg_u32 s98, 0
	s_cbranch_scc1 .Lsplit4_go2
	s_mov_b64 s[100:101], exec
	v_readlane_b32 s99, v254, 6
	s_nop 3
	s_mov_b32 exec_lo, s99
	s_mov_b32 exec_hi, 0
	s_cbranch_execz .Lsplit4_join2
	v_mov_b32_e32 v240, 0x7000
	v_mov_b32_e32 v242, 0

.Lsplit4_go2:
	s_lshl_b32 s84, s84, 12
	v_or_b32_e32 v4, s7, v138
	s_or_b32 s84, s84, 0x1c000
	v_ashrrev_i32_e32 v5, 31, v4
	v_lshl_add_u64 v[4:5], s[84:85], 0, v[4:5]
	s_waitcnt lgkmcnt(0)
	v_lshlrev_b64 v[4:5], 7, v[4:5]
	v_lshl_add_u64 v[8:9], v[134:135], 0, v[4:5]
	ds_read_b128 v[4:7], v155
	s_waitcnt lgkmcnt(0)
	global_store_dwordx4 v[8:9], v[4:7], off sc1
	s_nop 1
	v_or_b32_e32 v4, s7, v147
	v_ashrrev_i32_e32 v5, 31, v4
	v_lshl_add_u64 v[4:5], s[84:85], 0, v[4:5]
	v_lshlrev_b64 v[4:5], 7, v[4:5]
	v_lshl_add_u64 v[8:9], v[134:135], 0, v[4:5]
	ds_read_b128 v[4:7], v155 offset:1152
	s_waitcnt lgkmcnt(0)
	global_store_dwordx4 v[8:9], v[4:7], off sc1
	s_nop 1
	v_or_b32_e32 v4, s7, v148
	v_ashrrev_i32_e32 v5, 31, v4
	v_lshl_add_u64 v[4:5], s[84:85], 0, v[4:5]
	v_lshlrev_b64 v[4:5], 7, v[4:5]
	v_lshl_add_u64 v[8:9], v[134:135], 0, v[4:5]
	ds_read_b128 v[4:7], v155 offset:2304
	s_waitcnt lgkmcnt(0)
	global_store_dwordx4 v[8:9], v[4:7], off sc1
	s_nop 1
	v_or_b32_e32 v4, s7, v149
	v_ashrrev_i32_e32 v5, 31, v4
	v_lshl_add_u64 v[4:5], s[84:85], 0, v[4:5]
	v_lshlrev_b64 v[4:5], 7, v[4:5]
	v_lshl_add_u64 v[8:9], v[134:135], 0, v[4:5]
	ds_read_b128 v[4:7], v155 offset:3456
	s_waitcnt lgkmcnt(0)
	global_store_dwordx4 v[8:9], v[4:7], off sc1
	s_nop 1
	s_and_saveexec_b64 s[86:87], s[68:69]
	s_cbranch_execz .LBB0_581
	s_lshl_b32 s7, s84, 2
	s_add_u32 s88, s33, s7
	s_addc_u32 s89, s2, 0
	v_ashrrev_i32_e32 v137, 31, v136
	v_lshl_add_u64 v[4:5], v[136:137], 2, s[88:89]
	global_store_dword v[4:5], v2, off sc1
	s_branch .LBB0_581
